# layer-0 out-projection epilogue: f32 residual loads software-pipelined one 16-row step ahead (two register sets) instead of 8 serialized load-wait steps
# baseline (speedup 1.0000x reference)
.LBB0_983:
	v_lshl_add_u64 v[126:127], v[176:177], 2, s[8:9]
	global_load_dwordx4 v[130:133], v[126:127], off offset:16
	global_load_dwordx4 v[134:137], v[126:127], off
	global_load_dwordx4 v[122:125], v[126:127], off offset:528
	s_nop 0
	global_load_dwordx4 v[126:129], v[126:127], off offset:512
	v_readlane_b32 s26, v254, 46
	v_readlane_b32 s27, v254, 47
	s_and_b64 vcc, exec, s[26:27]
	s_mov_b64 s[26:27], -1
	s_cbranch_vccnz .LBB0_985
	v_lshl_add_u64 v[148:149], v[176:177], 2, s[2:3]
	v_lshlrev_b64 v[146:147], 13, v[150:151]
	v_lshl_add_u64 v[146:147], v[148:149], 0, v[146:147]
	global_load_dwordx4 v[152:155], v[146:147], off offset:16
	global_load_dwordx4 v[156:159], v[146:147], off
	global_load_dwordx4 v[160:163], v[146:147], off offset:528
	global_load_dwordx4 v[178:181], v[146:147], off offset:512
	v_or_b32_e32 v224, 16, v150
	v_ashrrev_i32_e32 v225, 31, v224
	v_lshlrev_b64 v[222:223], 13, v[224:225]
	v_lshl_add_u64 v[222:223], v[148:149], 0, v[222:223]
	global_load_dwordx4 v[206:209], v[222:223], off offset:16
	global_load_dwordx4 v[210:213], v[222:223], off
	global_load_dwordx4 v[214:217], v[222:223], off offset:528
	global_load_dwordx4 v[218:221], v[222:223], off offset:512
	v_lshlrev_b64 v[146:147], 12, v[150:151]
	s_mov_b64 s[26:27], 0
	s_waitcnt vmcnt(4)
	v_pk_fma_f32 v[164:165], v[140:141], v[132:133], v[154:155]
	v_pk_fma_f32 v[156:157], v[142:143], v[134:135], v[156:157]
	v_pk_fma_f32 v[158:159], v[144:145], v[136:137], v[158:159]
	v_pk_fma_f32 v[154:155], v[138:139], v[130:131], v[152:153]
	v_cvt_pk_bf16_f32 v152, v156, v157
	v_lshl_add_u64 v[156:157], s[0:1], 0, v[146:147]
	v_lshlrev_b64 v[146:147], 1, v[176:177]
	v_cvt_pk_bf16_f32 v153, v158, v159
	v_cvt_pk_bf16_f32 v154, v154, v155
	v_cvt_pk_bf16_f32 v155, v164, v165
	v_lshl_add_u64 v[156:157], v[156:157], 0, v[146:147]
	global_store_dwordx4 v[156:157], v[152:155], off
	v_pk_fma_f32 v[158:159], v[108:109], v[124:125], v[162:163]
	v_pk_fma_f32 v[160:161], v[106:107], v[122:123], v[160:161]
	v_pk_fma_f32 v[154:155], v[116:117], v[128:129], v[180:181]
	v_pk_fma_f32 v[152:153], v[114:115], v[126:127], v[178:179]
	v_or_b32_e32 v164, 16, v150
	v_cvt_pk_bf16_f32 v152, v152, v153
	v_cvt_pk_bf16_f32 v153, v154, v155
	v_cvt_pk_bf16_f32 v154, v160, v161
	v_cvt_pk_bf16_f32 v155, v158, v159
	v_ashrrev_i32_e32 v165, 31, v164
	global_store_dwordx4 v[156:157], v[152:155], off offset:256
	s_nop 1
	v_or_b32_e32 v224, 32, v150
	v_ashrrev_i32_e32 v225, 31, v224
	v_lshlrev_b64 v[222:223], 13, v[224:225]
	v_lshl_add_u64 v[222:223], v[148:149], 0, v[222:223]
	global_load_dwordx4 v[152:155], v[222:223], off offset:16
	global_load_dwordx4 v[156:159], v[222:223], off
	global_load_dwordx4 v[160:163], v[222:223], off offset:528
	global_load_dwordx4 v[178:181], v[222:223], off offset:512
	v_lshlrev_b64 v[164:165], 12, v[164:165]
	s_waitcnt vmcnt(9)
	v_pk_fma_f32 v[182:183], v[112:113], v[132:133], v[208:209]
	s_waitcnt vmcnt(8)
	v_pk_fma_f32 v[210:211], v[118:119], v[134:135], v[210:211]
	v_pk_fma_f32 v[212:213], v[120:121], v[136:137], v[212:213]
	v_pk_fma_f32 v[208:209], v[110:111], v[130:131], v[206:207]
	v_cvt_pk_bf16_f32 v206, v210, v211
	v_lshl_add_u64 v[210:211], s[0:1], 0, v[164:165]
	v_cvt_pk_bf16_f32 v207, v212, v213
	v_cvt_pk_bf16_f32 v208, v208, v209
	v_cvt_pk_bf16_f32 v209, v182, v183
	v_lshl_add_u64 v[210:211], v[210:211], 0, v[146:147]
	global_store_dwordx4 v[210:211], v[206:209], off
	s_waitcnt vmcnt(8)
	v_pk_fma_f32 v[212:213], v[96:97], v[124:125], v[216:217]
	v_pk_fma_f32 v[214:215], v[94:95], v[122:123], v[214:215]
	s_waitcnt vmcnt(7)
	v_pk_fma_f32 v[208:209], v[104:105], v[128:129], v[220:221]
	v_pk_fma_f32 v[206:207], v[102:103], v[126:127], v[218:219]
	v_or_b32_e32 v164, 32, v150
	v_cvt_pk_bf16_f32 v206, v206, v207
	v_cvt_pk_bf16_f32 v207, v208, v209
	v_cvt_pk_bf16_f32 v208, v214, v215
	v_cvt_pk_bf16_f32 v209, v212, v213
	v_ashrrev_i32_e32 v165, 31, v164
	global_store_dwordx4 v[210:211], v[206:209], off offset:256
	s_nop 1
	v_or_b32_e32 v224, 48, v150
	v_ashrrev_i32_e32 v225, 31, v224
	v_lshlrev_b64 v[222:223], 13, v[224:225]
	v_lshl_add_u64 v[222:223], v[148:149], 0, v[222:223]
	global_load_dwordx4 v[206:209], v[222:223], off offset:16
	global_load_dwordx4 v[210:213], v[222:223], off
	global_load_dwordx4 v[214:217], v[222:223], off offset:528
	global_load_dwordx4 v[218:221], v[222:223], off offset:512
	v_lshlrev_b64 v[164:165], 12, v[164:165]
	s_waitcnt vmcnt(9)
	v_pk_fma_f32 v[182:183], v[92:93], v[132:133], v[154:155]
	s_waitcnt vmcnt(8)
	v_pk_fma_f32 v[156:157], v[98:99], v[134:135], v[156:157]
	v_pk_fma_f32 v[158:159], v[100:101], v[136:137], v[158:159]
	v_pk_fma_f32 v[154:155], v[90:91], v[130:131], v[152:153]
	v_cvt_pk_bf16_f32 v152, v156, v157
	v_lshl_add_u64 v[156:157], s[0:1], 0, v[164:165]
	v_cvt_pk_bf16_f32 v153, v158, v159
	v_cvt_pk_bf16_f32 v154, v154, v155
	v_cvt_pk_bf16_f32 v155, v182, v183
	v_lshl_add_u64 v[156:157], v[156:157], 0, v[146:147]
	global_store_dwordx4 v[156:157], v[152:155], off
	s_waitcnt vmcnt(8)
	v_pk_fma_f32 v[158:159], v[80:81], v[124:125], v[162:163]
	v_pk_fma_f32 v[160:161], v[78:79], v[122:123], v[160:161]
	s_waitcnt vmcnt(7)
	v_pk_fma_f32 v[154:155], v[88:89], v[128:129], v[180:181]
	v_pk_fma_f32 v[152:153], v[86:87], v[126:127], v[178:179]
	v_or_b32_e32 v164, 48, v150
	v_cvt_pk_bf16_f32 v152, v152, v153
	v_cvt_pk_bf16_f32 v153, v154, v155
	v_cvt_pk_bf16_f32 v154, v160, v161
	v_cvt_pk_bf16_f32 v155, v158, v159
	v_ashrrev_i32_e32 v165, 31, v164
	global_store_dwordx4 v[156:157], v[152:155], off offset:256
	s_nop 1
	v_add_u32_e32 v224, 0x80, v150
	v_ashrrev_i32_e32 v225, 31, v224
	v_lshlrev_b64 v[222:223], 13, v[224:225]
	v_lshl_add_u64 v[222:223], v[148:149], 0, v[222:223]
	global_load_dwordx4 v[152:155], v[222:223], off offset:16
	global_load_dwordx4 v[156:159], v[222:223], off
	global_load_dwordx4 v[160:163], v[222:223], off offset:528
	global_load_dwordx4 v[178:181], v[222:223], off offset:512
	v_lshlrev_b64 v[164:165], 12, v[164:165]
	s_waitcnt vmcnt(9)
	v_pk_fma_f32 v[182:183], v[76:77], v[132:133], v[208:209]
	s_waitcnt vmcnt(8)
	v_pk_fma_f32 v[210:211], v[82:83], v[134:135], v[210:211]
	v_pk_fma_f32 v[212:213], v[84:85], v[136:137], v[212:213]
	v_pk_fma_f32 v[208:209], v[74:75], v[130:131], v[206:207]
	v_cvt_pk_bf16_f32 v206, v210, v211
	v_lshl_add_u64 v[210:211], s[0:1], 0, v[164:165]
	v_cvt_pk_bf16_f32 v207, v212, v213
	v_cvt_pk_bf16_f32 v208, v208, v209
	v_cvt_pk_bf16_f32 v209, v182, v183
	v_lshl_add_u64 v[210:211], v[210:211], 0, v[146:147]
	global_store_dwordx4 v[210:211], v[206:209], off
	s_waitcnt vmcnt(8)
	v_pk_fma_f32 v[212:213], v[68:69], v[124:125], v[216:217]
	v_pk_fma_f32 v[214:215], v[66:67], v[122:123], v[214:215]
	s_waitcnt vmcnt(7)
	v_pk_fma_f32 v[208:209], v[72:73], v[128:129], v[220:221]
	v_pk_fma_f32 v[206:207], v[70:71], v[126:127], v[218:219]
	v_add_u32_e32 v164, 0x80, v150
	v_cvt_pk_bf16_f32 v206, v206, v207
	v_cvt_pk_bf16_f32 v207, v208, v209
	v_cvt_pk_bf16_f32 v208, v214, v215
	v_cvt_pk_bf16_f32 v209, v212, v213
	v_ashrrev_i32_e32 v165, 31, v164
	global_store_dwordx4 v[210:211], v[206:209], off offset:256
	s_nop 1
	v_add_u32_e32 v224, 0x90, v150
	v_ashrrev_i32_e32 v225, 31, v224
	v_lshlrev_b64 v[222:223], 13, v[224:225]
	v_lshl_add_u64 v[222:223], v[148:149], 0, v[222:223]
	global_load_dwordx4 v[206:209], v[222:223], off offset:16
	global_load_dwordx4 v[210:213], v[222:223], off
	global_load_dwordx4 v[214:217], v[222:223], off offset:528
	global_load_dwordx4 v[218:221], v[222:223], off offset:512
	v_lshlrev_b64 v[164:165], 12, v[164:165]
	s_waitcnt vmcnt(9)
	v_pk_fma_f32 v[182:183], v[60:61], v[132:133], v[154:155]
	s_waitcnt vmcnt(8)
	v_pk_fma_f32 v[156:157], v[62:63], v[134:135], v[156:157]
	v_pk_fma_f32 v[158:159], v[64:65], v[136:137], v[158:159]
	v_pk_fma_f32 v[154:155], v[58:59], v[130:131], v[152:153]
	v_cvt_pk_bf16_f32 v152, v156, v157
	v_lshl_add_u64 v[156:157], s[0:1], 0, v[164:165]
	v_cvt_pk_bf16_f32 v153, v158, v159
	v_cvt_pk_bf16_f32 v154, v154, v155
	v_cvt_pk_bf16_f32 v155, v182, v183
	v_lshl_add_u64 v[156:157], v[156:157], 0, v[146:147]
	global_store_dwordx4 v[156:157], v[152:155], off
	s_waitcnt vmcnt(8)
	v_pk_fma_f32 v[158:159], v[48:49], v[124:125], v[162:163]
	v_pk_fma_f32 v[160:161], v[46:47], v[122:123], v[160:161]
	s_waitcnt vmcnt(7)
	v_pk_fma_f32 v[154:155], v[56:57], v[128:129], v[180:181]
	v_pk_fma_f32 v[152:153], v[54:55], v[126:127], v[178:179]
	v_add_u32_e32 v164, 0x90, v150
	v_cvt_pk_bf16_f32 v152, v152, v153
	v_cvt_pk_bf16_f32 v153, v154, v155
	v_cvt_pk_bf16_f32 v154, v160, v161
	v_cvt_pk_bf16_f32 v155, v158, v159
	v_ashrrev_i32_e32 v165, 31, v164
	global_store_dwordx4 v[156:157], v[152:155], off offset:256
	s_nop 1
	v_add_u32_e32 v224, 0xa0, v150
	v_ashrrev_i32_e32 v225, 31, v224
	v_lshlrev_b64 v[222:223], 13, v[224:225]
	v_lshl_add_u64 v[222:223], v[148:149], 0, v[222:223]
	global_load_dwordx4 v[152:155], v[222:223], off offset:16
	global_load_dwordx4 v[156:159], v[222:223], off
	global_load_dwordx4 v[160:163], v[222:223], off offset:528
	global_load_dwordx4 v[178:181], v[222:223], off offset:512
	v_lshlrev_b64 v[164:165], 12, v[164:165]
	s_waitcnt vmcnt(9)
	v_pk_fma_f32 v[182:183], v[44:45], v[132:133], v[208:209]
	s_waitcnt vmcnt(8)
	v_pk_fma_f32 v[210:211], v[50:51], v[134:135], v[210:211]
	v_pk_fma_f32 v[212:213], v[52:53], v[136:137], v[212:213]
	v_pk_fma_f32 v[208:209], v[42:43], v[130:131], v[206:207]
	v_cvt_pk_bf16_f32 v206, v210, v211
	v_lshl_add_u64 v[210:211], s[0:1], 0, v[164:165]
	v_cvt_pk_bf16_f32 v207, v212, v213
	v_cvt_pk_bf16_f32 v208, v208, v209
	v_cvt_pk_bf16_f32 v209, v182, v183
	v_lshl_add_u64 v[210:211], v[210:211], 0, v[146:147]
	global_store_dwordx4 v[210:211], v[206:209], off
	s_waitcnt vmcnt(8)
	v_pk_fma_f32 v[212:213], v[32:33], v[124:125], v[216:217]
	v_pk_fma_f32 v[214:215], v[30:31], v[122:123], v[214:215]
	s_waitcnt vmcnt(7)
	v_pk_fma_f32 v[208:209], v[40:41], v[128:129], v[220:221]
	v_pk_fma_f32 v[206:207], v[38:39], v[126:127], v[218:219]
	v_add_u32_e32 v164, 0xa0, v150
	v_cvt_pk_bf16_f32 v206, v206, v207
	v_cvt_pk_bf16_f32 v207, v208, v209
	v_cvt_pk_bf16_f32 v208, v214, v215
	v_cvt_pk_bf16_f32 v209, v212, v213
	v_ashrrev_i32_e32 v165, 31, v164
	global_store_dwordx4 v[210:211], v[206:209], off offset:256
	s_nop 1
	v_lshlrev_b64 v[164:165], 12, v[164:165]
	s_waitcnt vmcnt(5)
	v_pk_fma_f32 v[182:183], v[28:29], v[132:133], v[154:155]
	s_waitcnt vmcnt(4)
	v_pk_fma_f32 v[156:157], v[34:35], v[134:135], v[156:157]
	v_pk_fma_f32 v[158:159], v[36:37], v[136:137], v[158:159]
	v_pk_fma_f32 v[154:155], v[26:27], v[130:131], v[152:153]
	v_cvt_pk_bf16_f32 v152, v156, v157
	v_lshl_add_u64 v[156:157], s[0:1], 0, v[164:165]
	v_cvt_pk_bf16_f32 v153, v158, v159
	v_cvt_pk_bf16_f32 v154, v154, v155
	v_cvt_pk_bf16_f32 v155, v182, v183
	v_lshl_add_u64 v[156:157], v[156:157], 0, v[146:147]
	global_store_dwordx4 v[156:157], v[152:155], off
	s_waitcnt vmcnt(4)
	v_pk_fma_f32 v[158:159], v[16:17], v[124:125], v[162:163]
	v_pk_fma_f32 v[160:161], v[14:15], v[122:123], v[160:161]
	s_waitcnt vmcnt(3)
	v_pk_fma_f32 v[154:155], v[24:25], v[128:129], v[180:181]
	v_pk_fma_f32 v[152:153], v[22:23], v[126:127], v[178:179]
	s_nop 0
	v_cvt_pk_bf16_f32 v152, v152, v153
	v_cvt_pk_bf16_f32 v153, v154, v155
	v_cvt_pk_bf16_f32 v154, v160, v161
	v_cvt_pk_bf16_f32 v155, v158, v159
	global_store_dwordx4 v[156:157], v[152:155], off offset:256
	s_nop 1
	v_add_u32_e32 v152, 0xb0, v150
	v_ashrrev_i32_e32 v153, 31, v152
	v_lshlrev_b64 v[154:155], 13, v[152:153]
	v_lshl_add_u64 v[148:149], v[148:149], 0, v[154:155]
	global_load_dwordx4 v[154:157], v[148:149], off offset:16
	global_load_dwordx4 v[158:161], v[148:149], off
	global_load_dwordx4 v[162:165], v[148:149], off offset:528
	global_load_dwordx4 v[178:181], v[148:149], off offset:512
	v_lshlrev_b64 v[152:153], 12, v[152:153]
	s_waitcnt vmcnt(2)
	v_pk_fma_f32 v[148:149], v[20:21], v[136:137], v[160:161]
	v_pk_fma_f32 v[158:159], v[18:19], v[134:135], v[158:159]
	v_pk_fma_f32 v[160:161], v[12:13], v[132:133], v[156:157]
	v_pk_fma_f32 v[156:157], v[10:11], v[130:131], v[154:155]
	v_cvt_pk_bf16_f32 v155, v148, v149
	v_lshl_add_u64 v[148:149], s[0:1], 0, v[152:153]
	v_cvt_pk_bf16_f32 v154, v158, v159
	v_cvt_pk_bf16_f32 v156, v156, v157
	v_cvt_pk_bf16_f32 v157, v160, v161
	v_lshl_add_u64 v[146:147], v[148:149], 0, v[146:147]
	global_store_dwordx4 v[146:147], v[154:157], off
	s_waitcnt vmcnt(1)
	v_pk_fma_f32 v[148:149], v[8:9], v[128:129], v[180:181]
	v_pk_fma_f32 v[146:147], v[6:7], v[126:127], v[178:179]
	v_pk_fma_f32 v[156:157], v[2:3], v[122:123], v[162:163]
	v_pk_fma_f32 v[154:155], v[4:5], v[124:125], v[164:165]
	v_cvt_pk_bf16_f32 v146, v146, v147
	v_cvt_pk_bf16_f32 v147, v148, v149
	v_cvt_pk_bf16_f32 v148, v156, v157
